# idx job setup: redundant reload of the same 16 kernel-argument dwords (and its exposed scalar round trip) removed
# speedup vs baseline: 1.0018x; 1.0018x over previous
; DI void idx_job(const Params& p, int b, int qg, unsigned char* smem) {
;     ...
;   const int t0 = qg * 16, ntile = qg + 1, tq = t0 + lm;
;   const bool selall = tq + 1 <= 256;
;   bf16x8 qf[8];
;   float wq[8];
;   {
;     const u16* qr = p.qix + (size_t)(b * TP + tq) * 256 + lg * 8;
;     const float* wr = p.wix + (size_t)(b * TP + tq) * 8;
; #pragma unroll
;     for (int j = 0; j < 8; ++j) { qf[j] = *(const bf16x8*)(qr + j * 32); wq[j] = wr[j]; }
;   }
;   for (int i = tid; i < 8192 + 2112; i += 256) hist[i] = 0u;
;   if (tid < 80) ccnt[tid] = 0u;
;   __syncthreads();
;   const u16* kbase = p.kix + (size_t)b * TP * 32;
;   const f32x4 z4 = {0.f, 0.f, 0.f, 0.f};
;   const u16* kp = kbase + (size_t)lm * 32 + lg * 8;
.Lidxsc_lo:
	s_mul_i32 s88, s88, 0x42000
	s_add_u32 s90, s90, s88
	s_addc_u32 s91, s91, 0
	s_sub_u32 s92, s90, 0x2000
	s_subb_u32 s93, s91, 0
	s_sub_u32 s94, s90, 0x1000
	s_subb_u32 s95, s91, 0
	v_lshl_add_u64 v[248:249], s[90:91], 0, v[250:251]
	v_lshl_add_u64 v[2:3], s[70:71], 0, v[2:3]
	v_and_b32_e32 v4, 48, v86
	v_mov_b32_e32 v5, v1
	v_lshl_add_u64 v[10:11], v[2:3], 0, v[4:5]
	v_lshlrev_b64 v[2:3], 5, v[0:1]
	v_lshl_add_u64 v[6:7], s[74:75], 0, v[2:3]
	global_load_dwordx4 v[38:41], v[10:11], off
	global_load_dwordx4 v[34:37], v[10:11], off offset:64
	global_load_dwordx4 v[2:5], v[6:7], off offset:16
	s_nop 0
	global_load_dwordx4 v[6:9], v[6:7], off
	s_nop 0
	global_load_dwordx4 v[30:33], v[10:11], off offset:128
	global_load_dwordx4 v[26:29], v[10:11], off offset:192
	global_load_dwordx4 v[22:25], v[10:11], off offset:256
	global_load_dwordx4 v[18:21], v[10:11], off offset:320
	global_load_dwordx4 v[14:17], v[10:11], off offset:384
	s_nop 0
	global_load_dwordx4 v[10:13], v[10:11], off offset:448
	v_add_u32_e32 v136, 0xffffff00, v86
	v_lshl_add_u32 v137, v86, 2, v96
	v_mov_b32_e32 v158, 0
	v_mov_b32_e32 v159, 0
	v_mov_b32_e32 v160, 0
	v_mov_b32_e32 v161, 0
	v_lshl_add_u32 v43, v86, 4, v96
	ds_write_b128 v43, v[158:161]
	ds_write_b128 v43, v[158:161] offset:4096
	ds_write_b128 v43, v[158:161] offset:8192
	ds_write_b128 v43, v[158:161] offset:12288
	ds_write_b128 v43, v[158:161] offset:16384
	ds_write_b128 v43, v[158:161] offset:20480
	ds_write_b128 v43, v[158:161] offset:24576
	ds_write_b128 v43, v[158:161] offset:28672
	ds_write_b128 v43, v[158:161] offset:32768
	ds_write_b128 v43, v[158:161] offset:36864
	v_cmp_gt_u32_e64 s[4:5], 16, v86
	s_and_saveexec_b64 s[2:3], s[4:5]
	ds_write_b128 v43, v[158:161] offset:40960
	s_or_b64 exec, exec, s[2:3]
	v_bfe_u32 v54, v86, 4, 2
	s_movk_i32 s2, 0x50
	v_and_b32_e32 v141, 63, v86
	v_mul_u32_u24_e32 v89, 0x1080, v42
	v_lshlrev_b32_e32 v43, 3, v54
	v_cmp_gt_i32_e32 vcc, s2, v86
	s_and_saveexec_b64 s[2:3], vcc
	v_lshl_add_u32 v0, v86, 2, v96
	ds_write_b32 v0, v1 offset:49408
	s_or_b64 exec, exec, s[2:3]
	s_waitcnt lgkmcnt(0)
	s_barrier
	v_mul_u32_u24_e32 v0, 0x21000, v42
	v_ashrrev_i32_e32 v109, 6, v86
	v_lshlrev_b32_e32 v0, 1, v0
	v_cmp_le_i32_e32 vcc, v109, v97
	s_waitcnt lgkmcnt(0)
	v_lshl_add_u64 v[44:45], s[72:73], 0, v[0:1]
	v_lshlrev_b32_e32 v0, 6, v88
	v_lshl_add_u64 v[44:45], v[44:45], 0, v[0:1]
	v_lshlrev_b32_e32 v0, 1, v43
	v_cndmask_b32_e32 v42, 0, v109, vcc
	v_lshl_add_u64 v[90:91], v[44:45], 0, v[0:1]
	v_ashrrev_i32_e32 v43, 31, v42
	v_add_u32_e32 v0, 4, v109
	v_lshlrev_b64 v[42:43], 10, v[42:43]
	v_cmp_le_i32_e32 vcc, v0, v97
	v_lshl_add_u64 v[92:93], v[90:91], 0, v[42:43]
	v_mov_b32_e32 v110, v0
	v_cndmask_b32_e32 v42, 0, v0, vcc
	v_ashrrev_i32_e32 v43, 31, v42
	v_lshlrev_b64 v[42:43], 10, v[42:43]
	v_lshl_add_u64 v[94:95], v[90:91], 0, v[42:43]
	global_load_dwordx4 v[42:45], v[92:93], off
	global_load_dwordx4 v[50:53], v[94:95], off
	v_cmp_lt_i32_e32 vcc, v0, v97
	v_mov_b32_e32 v111, v109
	s_and_saveexec_b64 s[2:3], vcc
	s_cbranch_execz .LBB0_398
	v_mov_b32_e32 v55, v88
	s_waitcnt vmcnt(8)
	v_mov_b32_e32 v56, v8
	v_mov_b32_e32 v57, v8
	v_mov_b32_e32 v58, v9
	v_mov_b32_e32 v59, v9
	v_mov_b32_e32 v60, v2
	v_mov_b32_e32 v61, v2
	v_mov_b32_e32 v62, v3
	v_mov_b32_e32 v63, v3
	v_mov_b32_e32 v64, v4
	v_mov_b32_e32 v65, v4
	v_mov_b32_e32 v66, v5
	v_mov_b32_e32 v67, v5
	s_mov_b64 s[6:7], 0
	v_mov_b32_e32 v111, v109
	s_waitcnt vmcnt(0)
